# MLA attention: K/V tile park (LDS writes of tile u+1 and loads of tile u+2) moved from the interval head into the MFMA shadow of the QK and PV segments (counted lgkmcnt waits re-derived)
# baseline (speedup 1.0000x reference)
.LBB0_518:
	s_lshr_b32 s78, s71, 1
	s_mov_b32 s101, 0
	s_bitcmp1_b32 s71, 0
	s_cbranch_scc0 .LBB0_523
	s_cmp_gt_u32 s71, 1
	s_cbranch_scc0 .LBB0_523
	s_add_i32 s35, s78, 1
	s_cmp_lt_u32 s35, s70
	s_cselect_b32 s101, 1, 0
.LBB0_523:
	s_cmp_eq_u32 s100, 0
	s_cbranch_scc0 .Lyturn_M
	s_mov_b32 s100, 1
	s_cmp_ge_u32 s98, s70
	s_cbranch_scc1 .LBB0_517
	s_mov_b32 s72, s98
	s_add_i32 s98, s98, 1
	s_bitcmp1_b32 s72, 0
	s_cselect_b32 s72, 0xb400, 0
	v_add_u32_e32 v0, s72, v209
	ds_read_b128 v[166:169], v0
	ds_read_b128 v[170:173], v0 offset:32
	ds_read_b128 v[174:177], v0 offset:64
	ds_read_b128 v[178:181], v0 offset:96
	ds_read_b128 v[242:245], v0 offset:128
	ds_read_b128 v[246:249], v0 offset:160
	ds_read_b128 v[250:253], v0 offset:192
	ds_read_b128 v[204:207], v0 offset:224
	v_xor_b32_e32 v66, 0x80000000, v240
	v_mov_b32_e32 v67, v66
	v_mov_b32_e32 v68, v66
	v_mov_b32_e32 v69, v66
	v_mov_b32_e32 v70, v66
	v_mov_b32_e32 v71, v66
	v_mov_b32_e32 v72, v66
	v_mov_b32_e32 v73, v66
	v_mov_b32_e32 v74, v66
	v_mov_b32_e32 v75, v66
	v_mov_b32_e32 v76, v66
	v_mov_b32_e32 v77, v66
	v_mov_b32_e32 v78, v66
	v_mov_b32_e32 v79, v66
	v_mov_b32_e32 v80, v66
	v_mov_b32_e32 v81, v66
	s_waitcnt lgkmcnt(7)
	s_nop 0
	v_mfma_f32_32x32x16_bf16 v[82:97], v[166:169], v[98:101], v[66:81]
	s_waitcnt lgkmcnt(6)
	v_mfma_f32_32x32x16_bf16 v[82:97], v[170:173], v[102:105], v[82:97]
	s_waitcnt lgkmcnt(5)
	v_mfma_f32_32x32x16_bf16 v[82:97], v[174:177], v[106:109], v[82:97]
	s_waitcnt lgkmcnt(4)
	v_mfma_f32_32x32x16_bf16 v[82:97], v[178:181], v[110:113], v[82:97]
	ds_read_b128 v[166:169], v0 offset:256
	ds_read_b128 v[170:173], v0 offset:288
	ds_read_b128 v[174:177], v0 offset:320
	ds_read_b128 v[178:181], v0 offset:352
	s_waitcnt lgkmcnt(7)
	v_mfma_f32_32x32x16_bf16 v[82:97], v[242:245], v[114:117], v[82:97]
	s_waitcnt lgkmcnt(6)
	v_mfma_f32_32x32x16_bf16 v[82:97], v[246:249], v[118:121], v[82:97]
	s_waitcnt lgkmcnt(5)
	v_mfma_f32_32x32x16_bf16 v[82:97], v[250:253], v[122:125], v[82:97]
	s_waitcnt lgkmcnt(4)
	v_mfma_f32_32x32x16_bf16 v[82:97], v[204:207], v[126:129], v[82:97]
	ds_read_b128 v[204:207], v0 offset:12800
	ds_read_b128 v[242:245], v0 offset:12832
	ds_read_b128 v[246:249], v0 offset:12864
	ds_read_b128 v[250:253], v0 offset:12896
	s_waitcnt lgkmcnt(7)
	v_mfma_f32_32x32x16_bf16 v[82:97], v[166:169], v[130:133], v[82:97]
	s_waitcnt lgkmcnt(6)
	v_mfma_f32_32x32x16_bf16 v[82:97], v[170:173], v[134:137], v[82:97]
	s_waitcnt lgkmcnt(5)
	v_mfma_f32_32x32x16_bf16 v[82:97], v[174:177], v[138:141], v[82:97]
	s_waitcnt lgkmcnt(4)
	v_mfma_f32_32x32x16_bf16 v[82:97], v[178:181], v[142:145], v[82:97]
	ds_read_b128 v[166:169], v0 offset:12928
	ds_read_b128 v[170:173], v0 offset:12960
	ds_read_b128 v[174:177], v0 offset:12992
	ds_read_b128 v[178:181], v0 offset:13024
	s_waitcnt lgkmcnt(7)
	v_mfma_f32_32x32x16_bf16 v[66:81], v[204:207], v[98:101], v[66:81]
	s_waitcnt lgkmcnt(6)
	v_mfma_f32_32x32x16_bf16 v[66:81], v[242:245], v[102:105], v[66:81]
	s_waitcnt lgkmcnt(5)
	v_mfma_f32_32x32x16_bf16 v[66:81], v[246:249], v[106:109], v[66:81]
	s_waitcnt lgkmcnt(4)
	v_mfma_f32_32x32x16_bf16 v[66:81], v[250:253], v[110:113], v[66:81]
	ds_read_b128 v[204:207], v0 offset:13056
	ds_read_b128 v[242:245], v0 offset:13088
	ds_read_b128 v[246:249], v0 offset:13120
	ds_read_b128 v[250:253], v0 offset:13152
	s_cmp_eq_u32 s101, 1
	s_cbranch_scc1 .Lxpark_M
	s_waitcnt lgkmcnt(7)
	v_mfma_f32_32x32x16_bf16 v[66:81], v[166:169], v[114:117], v[66:81]
	s_waitcnt lgkmcnt(6)
	v_mfma_f32_32x32x16_bf16 v[66:81], v[170:173], v[118:121], v[66:81]
	s_waitcnt lgkmcnt(5)
	v_mfma_f32_32x32x16_bf16 v[66:81], v[174:177], v[122:125], v[66:81]
	s_waitcnt lgkmcnt(4)
	v_mfma_f32_32x32x16_bf16 v[66:81], v[178:181], v[126:129], v[66:81]
	s_waitcnt lgkmcnt(3)
	v_mfma_f32_32x32x16_bf16 v[66:81], v[204:207], v[130:133], v[66:81]
	s_waitcnt lgkmcnt(2)
	v_mfma_f32_32x32x16_bf16 v[66:81], v[242:245], v[134:137], v[66:81]
	s_waitcnt lgkmcnt(1)
	v_mfma_f32_32x32x16_bf16 v[66:81], v[246:249], v[138:141], v[66:81]
	s_waitcnt lgkmcnt(0)
	v_mfma_f32_32x32x16_bf16 v[66:81], v[250:253], v[142:145], v[66:81]
	s_branch .LBB0_525
.Lxpark_M:
	s_add_i32 s35, s78, 1
	s_bitcmp1_b32 s35, 0
	s_cselect_b32 s35, 0xb400, 0
	s_add_i32 s35, s35, 0
	v_add3_u32 v0, s35, v227, v218
	s_waitcnt vmcnt(4)
	ds_write_b128 v0, v[146:149]
	v_add3_u32 v0, s35, v228, v220
	s_waitcnt vmcnt(3)
	ds_write_b128 v0, v[150:153]
	v_add3_u32 v0, s35, v229, v226
	s_waitcnt vmcnt(2)
	ds_write_b128 v0, v[154:157] offset:256
	v_add3_u32 v0, s35, v230, v218
	s_waitcnt vmcnt(1)
	ds_write_b128 v0, v[158:161] offset:25600
	v_add3_u32 v0, s35, v201, v220
	s_waitcnt vmcnt(0)
	ds_write_b128 v0, v[162:165] offset:25600
	s_waitcnt lgkmcnt(12)
	v_mfma_f32_32x32x16_bf16 v[66:81], v[166:169], v[114:117], v[66:81]
	s_waitcnt lgkmcnt(11)
	v_mfma_f32_32x32x16_bf16 v[66:81], v[170:173], v[118:121], v[66:81]
	s_waitcnt lgkmcnt(10)
	v_mfma_f32_32x32x16_bf16 v[66:81], v[174:177], v[122:125], v[66:81]
	s_waitcnt lgkmcnt(9)
	v_mfma_f32_32x32x16_bf16 v[66:81], v[178:181], v[126:129], v[66:81]
	s_waitcnt lgkmcnt(8)
	v_mfma_f32_32x32x16_bf16 v[66:81], v[204:207], v[130:133], v[66:81]
	s_waitcnt lgkmcnt(7)
	v_mfma_f32_32x32x16_bf16 v[66:81], v[242:245], v[134:137], v[66:81]
	s_waitcnt lgkmcnt(6)
	v_mfma_f32_32x32x16_bf16 v[66:81], v[246:249], v[138:141], v[66:81]
	s_waitcnt lgkmcnt(5)
	v_mfma_f32_32x32x16_bf16 v[66:81], v[250:253], v[142:145], v[66:81]
	s_add_i32 s35, s78, 2
	s_cmp_ge_u32 s35, s70
	s_cbranch_scc1 .Lnold_x
	s_sub_i32 s72, s35, s68
	s_min_u32 s72, s35, s72
	s_lshl_b32 s77, s72, 6
	s_cmp_lt_u32 s35, s68
	v_add_u32_e32 v0, s77, v199
	s_waitcnt vmcnt(3)
	v_add_u32_e32 v150, s77, v219
	s_cselect_b32 s73, s17, s9
	s_cselect_b32 s72, s16, s8
	v_lshl_add_u32 v0, v0, 13, v218
	s_waitcnt vmcnt(0)
	v_lshl_add_u32 v162, v150, 13, v220
	v_add_u32_e32 v154, s77, v221
	global_load_dwordx4 v[146:149], v0, s[72:73]
	global_load_dwordx4 v[150:153], v162, s[72:73]
	s_cselect_b32 s73, s19, s11
	s_cselect_b32 s72, s18, s10
	v_lshl_or_b32 v154, v154, 7, v226
	global_load_dwordx4 v[154:157], v154, s[72:73]
	s_cselect_b32 s73, s21, s15
	s_cselect_b32 s72, s20, s14
	global_load_dwordx4 v[158:161], v0, s[72:73]
	s_nop 0
	global_load_dwordx4 v[162:165], v162, s[72:73]
.Lnold_x:
.LBB0_525:
	s_branch .LBB0_517

.LBB0_534:
	ds_read_b64_tr_b16 v[204:205], v241 offset:30720
	ds_read_b64_tr_b16 v[242:243], v241 offset:30784
	ds_read_b64_tr_b16 v[246:247], v241 offset:30848
	ds_read_b64_tr_b16 v[250:251], v241 offset:30912
	ds_read_b64_tr_b16 v[206:207], v241 offset:33280
	ds_read_b64_tr_b16 v[244:245], v241 offset:33344
	ds_read_b64_tr_b16 v[248:249], v241 offset:33408
	ds_read_b64_tr_b16 v[252:253], v241 offset:33472
	v_exp_f32_e32 v82, v82
	v_exp_f32_e32 v83, v83
	v_exp_f32_e32 v84, v84
	v_exp_f32_e32 v85, v85
	v_exp_f32_e32 v86, v86
	v_exp_f32_e32 v87, v87
	v_exp_f32_e32 v88, v88
	v_exp_f32_e32 v89, v89
	v_cvt_pk_bf16_f32 v194, v82, v83
	v_cvt_pk_bf16_f32 v195, v84, v85
	v_cvt_pk_bf16_f32 v196, v86, v87
	v_cvt_pk_bf16_f32 v197, v88, v89
	v_exp_f32_e32 v90, v90
	s_waitcnt lgkmcnt(11)
	v_mfma_f32_32x32x16_bf16 v[50:65], v[178:181], v[194:197], v[50:65]
	v_exp_f32_e32 v91, v91
	v_exp_f32_e32 v92, v92
	v_exp_f32_e32 v93, v93
	v_exp_f32_e32 v94, v94
	v_exp_f32_e32 v95, v95
	v_exp_f32_e32 v96, v96
	v_exp_f32_e32 v97, v97
	s_waitcnt lgkmcnt(10)
	v_mfma_f32_32x32x16_bf16 v[34:49], v[174:177], v[194:197], v[34:49]
	v_exp_f32_e32 v66, v66
	v_exp_f32_e32 v67, v67
	v_exp_f32_e32 v68, v68
	v_exp_f32_e32 v69, v69
	v_exp_f32_e32 v70, v70
	v_exp_f32_e32 v71, v71
	v_exp_f32_e32 v72, v72
	s_waitcnt lgkmcnt(9)
	v_mfma_f32_32x32x16_bf16 v[18:33], v[170:173], v[194:197], v[18:33]
	v_exp_f32_e32 v73, v73
	s_waitcnt lgkmcnt(8)
	v_mfma_f32_32x32x16_bf16 v[2:17], v[166:169], v[194:197], v[2:17]
	ds_read_b64_tr_b16 v[166:167], v241 offset:35840
	ds_read_b64_tr_b16 v[170:171], v241 offset:35904
	ds_read_b64_tr_b16 v[174:175], v241 offset:35968
	ds_read_b64_tr_b16 v[178:179], v241 offset:36032
	ds_read_b64_tr_b16 v[168:169], v241 offset:38400
	ds_read_b64_tr_b16 v[172:173], v241 offset:38464
	ds_read_b64_tr_b16 v[176:177], v241 offset:38528
	ds_read_b64_tr_b16 v[180:181], v241 offset:38592
	v_cvt_pk_bf16_f32 v194, v90, v91
	v_cvt_pk_bf16_f32 v195, v92, v93
	v_cvt_pk_bf16_f32 v196, v94, v95
	v_cvt_pk_bf16_f32 v197, v96, v97
	v_exp_f32_e32 v74, v74
	s_waitcnt lgkmcnt(11)
	v_mfma_f32_32x32x16_bf16 v[50:65], v[204:207], v[194:197], v[50:65]
	v_exp_f32_e32 v75, v75
	v_exp_f32_e32 v76, v76
	v_exp_f32_e32 v77, v77
	v_exp_f32_e32 v78, v78
	v_exp_f32_e32 v79, v79
	v_exp_f32_e32 v80, v80
	v_exp_f32_e32 v81, v81
	s_waitcnt lgkmcnt(10)
	v_mfma_f32_32x32x16_bf16 v[34:49], v[242:245], v[194:197], v[34:49]
	s_waitcnt lgkmcnt(9)
	v_mfma_f32_32x32x16_bf16 v[18:33], v[246:249], v[194:197], v[18:33]
	s_waitcnt lgkmcnt(8)
	v_mfma_f32_32x32x16_bf16 v[2:17], v[250:253], v[194:197], v[2:17]
	ds_read_b64_tr_b16 v[194:195], v241 offset:40960
	ds_read_b64_tr_b16 v[204:205], v241 offset:41024
	ds_read_b64_tr_b16 v[242:243], v241 offset:41088
	ds_read_b64_tr_b16 v[246:247], v241 offset:41152
	ds_read_b64_tr_b16 v[196:197], v241 offset:43520
	ds_read_b64_tr_b16 v[206:207], v241 offset:43584
	ds_read_b64_tr_b16 v[244:245], v241 offset:43648
	ds_read_b64_tr_b16 v[248:249], v241 offset:43712
	v_cvt_pk_bf16_f32 v250, v66, v67
	v_cvt_pk_bf16_f32 v251, v68, v69
	v_cvt_pk_bf16_f32 v252, v70, v71
	v_cvt_pk_bf16_f32 v253, v72, v73
	s_waitcnt lgkmcnt(11)
	v_mfma_f32_32x32x16_bf16 v[50:65], v[166:169], v[250:253], v[50:65]
	s_waitcnt lgkmcnt(10)
	v_mfma_f32_32x32x16_bf16 v[34:49], v[170:173], v[250:253], v[34:49]
	s_waitcnt lgkmcnt(9)
	v_mfma_f32_32x32x16_bf16 v[18:33], v[174:177], v[250:253], v[18:33]
	s_waitcnt lgkmcnt(8)
	v_mfma_f32_32x32x16_bf16 v[2:17], v[178:181], v[250:253], v[2:17]
	s_cmp_eq_u32 s101, 1
	s_cbranch_scc1 .Lypark_M
	v_cvt_pk_bf16_f32 v166, v74, v75
	v_cvt_pk_bf16_f32 v167, v76, v77
	v_cvt_pk_bf16_f32 v168, v78, v79
	v_cvt_pk_bf16_f32 v169, v80, v81
	s_waitcnt lgkmcnt(3)
	v_mfma_f32_32x32x16_bf16 v[50:65], v[194:197], v[166:169], v[50:65]
	s_waitcnt lgkmcnt(2)
	v_mfma_f32_32x32x16_bf16 v[34:49], v[204:207], v[166:169], v[34:49]
	s_waitcnt lgkmcnt(1)
	v_mfma_f32_32x32x16_bf16 v[18:33], v[242:245], v[166:169], v[18:33]
	s_waitcnt lgkmcnt(0)
	v_mfma_f32_32x32x16_bf16 v[2:17], v[246:249], v[166:169], v[2:17]
	s_branch .Lyjoin_M
.Lypark_M:
	s_add_i32 s35, s78, 1
	s_bitcmp1_b32 s35, 0
	s_cselect_b32 s35, 0xb400, 0
	s_add_i32 s35, s35, 0
	v_add3_u32 v0, s35, v227, v218
	s_waitcnt vmcnt(4)
	ds_write_b128 v0, v[146:149]
	v_add3_u32 v0, s35, v228, v220
	s_waitcnt vmcnt(3)
	ds_write_b128 v0, v[150:153]
	v_add3_u32 v0, s35, v229, v226
	s_waitcnt vmcnt(2)
	ds_write_b128 v0, v[154:157] offset:256
	v_add3_u32 v0, s35, v230, v218
	s_waitcnt vmcnt(1)
	ds_write_b128 v0, v[158:161] offset:25600
	v_add3_u32 v0, s35, v201, v220
	s_waitcnt vmcnt(0)
	ds_write_b128 v0, v[162:165] offset:25600
	v_cvt_pk_bf16_f32 v166, v74, v75
	v_cvt_pk_bf16_f32 v167, v76, v77
	v_cvt_pk_bf16_f32 v168, v78, v79
	v_cvt_pk_bf16_f32 v169, v80, v81
	s_waitcnt lgkmcnt(8)
	v_mfma_f32_32x32x16_bf16 v[50:65], v[194:197], v[166:169], v[50:65]
	s_waitcnt lgkmcnt(7)
	v_mfma_f32_32x32x16_bf16 v[34:49], v[204:207], v[166:169], v[34:49]
	s_waitcnt lgkmcnt(6)
	v_mfma_f32_32x32x16_bf16 v[18:33], v[242:245], v[166:169], v[18:33]
	s_waitcnt lgkmcnt(5)
	v_mfma_f32_32x32x16_bf16 v[2:17], v[246:249], v[166:169], v[2:17]
	s_add_i32 s35, s78, 2
	s_cmp_ge_u32 s35, s70
	s_cbranch_scc1 .Lnold_y
	s_sub_i32 s72, s35, s68
	s_min_u32 s72, s35, s72
	s_lshl_b32 s77, s72, 6
	s_cmp_lt_u32 s35, s68
	v_add_u32_e32 v0, s77, v199
	s_waitcnt vmcnt(3)
	v_add_u32_e32 v150, s77, v219
	s_cselect_b32 s73, s17, s9
	s_cselect_b32 s72, s16, s8
	v_lshl_add_u32 v0, v0, 13, v218
	s_waitcnt vmcnt(0)
	v_lshl_add_u32 v162, v150, 13, v220
	v_add_u32_e32 v154, s77, v221
	global_load_dwordx4 v[146:149], v0, s[72:73]
	global_load_dwordx4 v[150:153], v162, s[72:73]
	s_cselect_b32 s73, s19, s11
	s_cselect_b32 s72, s18, s10
	v_lshl_or_b32 v154, v154, 7, v226
	global_load_dwordx4 v[154:157], v154, s[72:73]
	s_cselect_b32 s73, s21, s15
	s_cselect_b32 s72, s20, s14
	global_load_dwordx4 v[158:161], v0, s[72:73]
	s_nop 0
	global_load_dwordx4 v[162:165], v162, s[72:73]
.Lnold_y:
.Lyjoin_M:
	s_mov_b64 s[30:31], -1
	s_and_b64 vcc, exec, s[26:27]
	s_cbranch_vccz .LBB0_536
	s_setprio 0
	s_mov_b64 s[30:31], 0
